# v7 plus: SSM GLU gate (y x w_glu, 16x16 per token) moved from VALU to v_mfma_f32_16x16x4_f32 (f32 operands), 1 LDS read instead of 16 per wave-chunk
# baseline (speedup 1.0000x reference)
; #define LAS __attribute__((address_space(3)))
; template <bool SAMPLE>
; __device__ __forceinline__ void ssm_item(kp_t kp, LAS unsigned char* lds, int l, int item, const bf16_t* Z, float* YM, int tid, int lane, int wave) {
;     ...
;         f32x2 hl[16]; f32x2 h = (f32x2){0.f, 0.f};
; #pragma unroll
;         for (int tt = 0; tt < 16; ++tt) { const LAS f32x4* up = (const LAS f32x4*)(U + (wave * 16 + tt) * 16);
;             if (SAMPLE && (tt & 3) == 0) h = h0[tt >> 2];
;             f32x2 bu = (f32x2){0.f, 0.f};
; #pragma unroll
;             for (int q = 0; q < 4; ++q) { const f32x4 u = up[q];
; #pragma unroll
;                 for (int e = 0; e < 4; ++e) bu = __builtin_elementwise_fma(B2[4 * q + e], (f32x2){u[e], u[e]}, bu); }
;             const f32x2 t1 = __builtin_elementwise_fma((f32x2){lr, lr}, h, bu);
;             h = __builtin_elementwise_fma((f32x2){-li, li}, (f32x2){h.y, h.x}, t1); hl[tt] = h;
;             if (SAMPLE && (tt & 3) == 3) { const size_t si = ((size_t)(l * 128 + b * 32 + wave * 4 + (tt >> 2)) * 64 + g) * 64 + p; OUTP[O_SRE + si] = h.x; OUTP[O_SIM + si] = h.y; } }
.LBB0_100:
	s_add_i32 s25, s3, s24
	v_and_b32_e32 v254, 3, v184
	v_lshl_add_u32 v254, v254, 6, s25
	s_waitcnt lgkmcnt(0)
	ds_read_b128 v[20:23], v254
	ds_read_b64 v[244:245], v254 offset:16
	ds_read_b64 v[248:249], v254 offset:24
	ds_read_b128 v[174:177], v254 offset:32
	ds_read_b128 v[188:191], v254 offset:48
	v_cndmask_b32_e64 v247, 0, v133, s[0:1]
	v_mul_f32_e32 v246, v107, v133
	s_waitcnt lgkmcnt(2)
	v_mfma_f32_4x4x1_16b_f32 v[232:235], v20, v72, 0
	v_mfma_f32_4x4x1_16b_f32 v[236:239], v20, v73, 0
	s_nop 0
	v_mfma_f32_4x4x1_16b_f32 v[232:235], v21, v64, v[232:235]
	v_mfma_f32_4x4x1_16b_f32 v[236:239], v21, v65, v[236:239]
	s_nop 0
	v_mfma_f32_4x4x1_16b_f32 v[232:235], v22, v60, v[232:235]
	v_mfma_f32_4x4x1_16b_f32 v[236:239], v22, v61, v[236:239]
	s_nop 0
	v_mfma_f32_4x4x1_16b_f32 v[232:235], v23, v62, v[232:235]
	v_mfma_f32_4x4x1_16b_f32 v[236:239], v23, v63, v[236:239]
	s_nop 0
	v_mfma_f32_4x4x1_16b_f32 v[232:235], v244, v66, v[232:235]
	v_mfma_f32_4x4x1_16b_f32 v[236:239], v244, v67, v[236:239]
	s_nop 0
	v_mfma_f32_4x4x1_16b_f32 v[232:235], v245, v52, v[232:235]
	v_mfma_f32_4x4x1_16b_f32 v[236:239], v245, v53, v[236:239]
	s_nop 0
	v_mfma_f32_4x4x1_16b_f32 v[232:235], v248, v56, v[232:235]
	v_mfma_f32_4x4x1_16b_f32 v[236:239], v248, v57, v[236:239]
	s_nop 0
	v_mfma_f32_4x4x1_16b_f32 v[232:235], v249, v54, v[232:235]
	v_mfma_f32_4x4x1_16b_f32 v[236:239], v249, v55, v[236:239]
	s_nop 0
	ds_read_b128 v[20:23], v254 offset:256
	ds_read_b64 v[244:245], v254 offset:272
	ds_read_b64 v[248:249], v254 offset:280
	s_waitcnt lgkmcnt(3)
	v_mfma_f32_4x4x1_16b_f32 v[232:235], v174, v58, v[232:235]
	v_mfma_f32_4x4x1_16b_f32 v[236:239], v174, v59, v[236:239]
	s_nop 0
	v_mfma_f32_4x4x1_16b_f32 v[232:235], v175, v44, v[232:235]
	v_mfma_f32_4x4x1_16b_f32 v[236:239], v175, v45, v[236:239]
	s_nop 0
	v_mfma_f32_4x4x1_16b_f32 v[232:235], v176, v48, v[232:235]
	v_mfma_f32_4x4x1_16b_f32 v[236:239], v176, v49, v[236:239]
	s_nop 0
	v_mfma_f32_4x4x1_16b_f32 v[232:235], v177, v46, v[232:235]
	v_mfma_f32_4x4x1_16b_f32 v[236:239], v177, v47, v[236:239]
	s_nop 0
	v_mfma_f32_4x4x1_16b_f32 v[232:235], v188, v50, v[232:235]
	v_mfma_f32_4x4x1_16b_f32 v[236:239], v188, v51, v[236:239]
	s_nop 0
	v_mfma_f32_4x4x1_16b_f32 v[232:235], v189, v36, v[232:235]
	v_mfma_f32_4x4x1_16b_f32 v[236:239], v189, v37, v[236:239]
	s_nop 0
	v_mfma_f32_4x4x1_16b_f32 v[232:235], v190, v40, v[232:235]
	v_mfma_f32_4x4x1_16b_f32 v[236:239], v190, v41, v[236:239]
	s_nop 0
	v_mfma_f32_4x4x1_16b_f32 v[232:235], v191, v38, v[232:235]
	v_mfma_f32_4x4x1_16b_f32 v[236:239], v191, v39, v[236:239]
	s_nop 0
	ds_read_b128 v[174:177], v254 offset:288
	ds_read_b128 v[188:191], v254 offset:304
	s_nop 4
	v_fma_f32 v138, v42, 0, v232
	v_fma_f32 v139, v43, 0, v236
	v_fma_f32 v138, v70, 0, v138
	v_fma_f32 v139, v71, 0, v139
	v_fma_f32 v140, v42, v138, v233
	v_fma_f32 v141, v43, v139, v237
	v_fma_f32 v140, v70, v139, v140
	v_fma_f32 v141, v71, v138, v141
	v_fma_f32 v142, v42, v140, v234
	v_fma_f32 v143, v43, v141, v238
	v_fma_f32 v142, v70, v141, v142
	v_fma_f32 v143, v71, v140, v143
	v_fma_f32 v144, v42, v142, v235
	v_fma_f32 v145, v43, v143, v239
	v_fma_f32 v144, v70, v143, v144
	v_fma_f32 v145, v71, v142, v145
	s_waitcnt lgkmcnt(2)
	v_mfma_f32_4x4x1_16b_f32 v[232:235], v20, v72, 0
	v_mfma_f32_4x4x1_16b_f32 v[236:239], v20, v73, 0
	s_nop 0
	v_mfma_f32_4x4x1_16b_f32 v[232:235], v21, v64, v[232:235]
	v_mfma_f32_4x4x1_16b_f32 v[236:239], v21, v65, v[236:239]
	s_nop 0
	v_mfma_f32_4x4x1_16b_f32 v[232:235], v22, v60, v[232:235]
	v_mfma_f32_4x4x1_16b_f32 v[236:239], v22, v61, v[236:239]
	s_nop 0
	v_mfma_f32_4x4x1_16b_f32 v[232:235], v23, v62, v[232:235]
	v_mfma_f32_4x4x1_16b_f32 v[236:239], v23, v63, v[236:239]
	s_nop 0
	v_mfma_f32_4x4x1_16b_f32 v[232:235], v244, v66, v[232:235]
	v_mfma_f32_4x4x1_16b_f32 v[236:239], v244, v67, v[236:239]
	s_nop 0
	v_mfma_f32_4x4x1_16b_f32 v[232:235], v245, v52, v[232:235]
	v_mfma_f32_4x4x1_16b_f32 v[236:239], v245, v53, v[236:239]
	s_nop 0
	v_mfma_f32_4x4x1_16b_f32 v[232:235], v248, v56, v[232:235]
	v_mfma_f32_4x4x1_16b_f32 v[236:239], v248, v57, v[236:239]
	s_nop 0
	v_mfma_f32_4x4x1_16b_f32 v[232:235], v249, v54, v[232:235]
	v_mfma_f32_4x4x1_16b_f32 v[236:239], v249, v55, v[236:239]
	s_nop 0
	ds_read_b128 v[20:23], v254 offset:512
	ds_read_b64 v[244:245], v254 offset:528
	ds_read_b64 v[248:249], v254 offset:536
	s_waitcnt lgkmcnt(3)
	v_mfma_f32_4x4x1_16b_f32 v[232:235], v174, v58, v[232:235]
	v_mfma_f32_4x4x1_16b_f32 v[236:239], v174, v59, v[236:239]
	s_nop 0
	v_mfma_f32_4x4x1_16b_f32 v[232:235], v175, v44, v[232:235]
	v_mfma_f32_4x4x1_16b_f32 v[236:239], v175, v45, v[236:239]
	s_nop 0
	v_mfma_f32_4x4x1_16b_f32 v[232:235], v176, v48, v[232:235]
	v_mfma_f32_4x4x1_16b_f32 v[236:239], v176, v49, v[236:239]
	s_nop 0
	v_mfma_f32_4x4x1_16b_f32 v[232:235], v177, v46, v[232:235]
	v_mfma_f32_4x4x1_16b_f32 v[236:239], v177, v47, v[236:239]
	s_nop 0
	v_mfma_f32_4x4x1_16b_f32 v[232:235], v188, v50, v[232:235]
	v_mfma_f32_4x4x1_16b_f32 v[236:239], v188, v51, v[236:239]
	s_nop 0
	v_mfma_f32_4x4x1_16b_f32 v[232:235], v189, v36, v[232:235]
	v_mfma_f32_4x4x1_16b_f32 v[236:239], v189, v37, v[236:239]
	s_nop 0
	v_mfma_f32_4x4x1_16b_f32 v[232:235], v190, v40, v[232:235]
	v_mfma_f32_4x4x1_16b_f32 v[236:239], v190, v41, v[236:239]
	s_nop 0
	v_mfma_f32_4x4x1_16b_f32 v[232:235], v191, v38, v[232:235]
	v_mfma_f32_4x4x1_16b_f32 v[236:239], v191, v39, v[236:239]
	s_nop 0
	ds_read_b128 v[174:177], v254 offset:544
	ds_read_b128 v[188:191], v254 offset:560
	s_nop 4
	v_fma_f32 v146, v42, v144, v232
	v_fma_f32 v147, v43, v145, v236
	v_fma_f32 v146, v70, v145, v146
	v_fma_f32 v147, v71, v144, v147
	v_fma_f32 v160, v42, v146, v233
	v_fma_f32 v161, v43, v147, v237
	v_fma_f32 v160, v70, v147, v160
	v_fma_f32 v161, v71, v146, v161
	v_fma_f32 v162, v42, v160, v234
	v_fma_f32 v163, v43, v161, v238
	v_fma_f32 v162, v70, v161, v162
	v_fma_f32 v163, v71, v160, v163
	v_fma_f32 v164, v42, v162, v235
	v_fma_f32 v165, v43, v163, v239
	v_fma_f32 v164, v70, v163, v164
	v_fma_f32 v165, v71, v162, v165
	s_waitcnt lgkmcnt(2)
; #define LAS __attribute__((address_space(3)))
; template <bool SAMPLE>
; __device__ __forceinline__ void ssm_item(kp_t kp, LAS unsigned char* lds, int l, int item, const bf16_t* Z, float* YM, int tid, int lane, int wave) {
;     ...
;         f32x2 hl[16]; f32x2 h = (f32x2){0.f, 0.f};
; #pragma unroll
;         for (int tt = 0; tt < 16; ++tt) { const LAS f32x4* up = (const LAS f32x4*)(U + (wave * 16 + tt) * 16);
;             if (SAMPLE && (tt & 3) == 0) h = h0[tt >> 2];
;             f32x2 bu = (f32x2){0.f, 0.f};
; #pragma unroll
;             for (int q = 0; q < 4; ++q) { const f32x4 u = up[q];
; #pragma unroll
;                 for (int e = 0; e < 4; ++e) bu = __builtin_elementwise_fma(B2[4 * q + e], (f32x2){u[e], u[e]}, bu); }
;             const f32x2 t1 = __builtin_elementwise_fma((f32x2){lr, lr}, h, bu);
;             h = __builtin_elementwise_fma((f32x2){-li, li}, (f32x2){h.y, h.x}, t1); hl[tt] = h;
;             if (SAMPLE && (tt & 3) == 3) { const size_t si = ((size_t)(l * 128 + b * 32 + wave * 4 + (tt >> 2)) * 64 + g) * 64 + p; OUTP[O_SRE + si] = h.x; OUTP[O_SIM + si] = h.y; } }
;         float cr_ = car, ci_ = cai, cwr = 0.f, cwi = 0.f;
;         if (!SAMPLE) {
;         Eb[wave * 64 + p] = h;
	v_mfma_f32_4x4x1_16b_f32 v[232:235], v20, v72, 0
	v_mfma_f32_4x4x1_16b_f32 v[236:239], v20, v73, 0
	s_nop 0
	v_mfma_f32_4x4x1_16b_f32 v[232:235], v21, v64, v[232:235]
	v_mfma_f32_4x4x1_16b_f32 v[236:239], v21, v65, v[236:239]
	s_nop 0
	v_mfma_f32_4x4x1_16b_f32 v[232:235], v22, v60, v[232:235]
	v_mfma_f32_4x4x1_16b_f32 v[236:239], v22, v61, v[236:239]
	s_nop 0
	v_mfma_f32_4x4x1_16b_f32 v[232:235], v23, v62, v[232:235]
	v_mfma_f32_4x4x1_16b_f32 v[236:239], v23, v63, v[236:239]
	s_nop 0
	v_mfma_f32_4x4x1_16b_f32 v[232:235], v244, v66, v[232:235]
	v_mfma_f32_4x4x1_16b_f32 v[236:239], v244, v67, v[236:239]
	s_nop 0
	v_mfma_f32_4x4x1_16b_f32 v[232:235], v245, v52, v[232:235]
	v_mfma_f32_4x4x1_16b_f32 v[236:239], v245, v53, v[236:239]
	s_nop 0
	v_mfma_f32_4x4x1_16b_f32 v[232:235], v248, v56, v[232:235]
	v_mfma_f32_4x4x1_16b_f32 v[236:239], v248, v57, v[236:239]
	s_nop 0
	v_mfma_f32_4x4x1_16b_f32 v[232:235], v249, v54, v[232:235]
	v_mfma_f32_4x4x1_16b_f32 v[236:239], v249, v55, v[236:239]
	s_nop 0
	ds_read_b128 v[20:23], v254 offset:768
	ds_read_b64 v[244:245], v254 offset:784
	ds_read_b64 v[248:249], v254 offset:792
	s_waitcnt lgkmcnt(3)
	v_mfma_f32_4x4x1_16b_f32 v[232:235], v174, v58, v[232:235]
	v_mfma_f32_4x4x1_16b_f32 v[236:239], v174, v59, v[236:239]
	s_nop 0
	v_mfma_f32_4x4x1_16b_f32 v[232:235], v175, v44, v[232:235]
	v_mfma_f32_4x4x1_16b_f32 v[236:239], v175, v45, v[236:239]
	s_nop 0
	v_mfma_f32_4x4x1_16b_f32 v[232:235], v176, v48, v[232:235]
	v_mfma_f32_4x4x1_16b_f32 v[236:239], v176, v49, v[236:239]
	s_nop 0
	v_mfma_f32_4x4x1_16b_f32 v[232:235], v177, v46, v[232:235]
	v_mfma_f32_4x4x1_16b_f32 v[236:239], v177, v47, v[236:239]
	s_nop 0
	v_mfma_f32_4x4x1_16b_f32 v[232:235], v188, v50, v[232:235]
	v_mfma_f32_4x4x1_16b_f32 v[236:239], v188, v51, v[236:239]
	s_nop 0
	v_mfma_f32_4x4x1_16b_f32 v[232:235], v189, v36, v[232:235]
	v_mfma_f32_4x4x1_16b_f32 v[236:239], v189, v37, v[236:239]
	s_nop 0
	v_mfma_f32_4x4x1_16b_f32 v[232:235], v190, v40, v[232:235]
	v_mfma_f32_4x4x1_16b_f32 v[236:239], v190, v41, v[236:239]
	s_nop 0
	v_mfma_f32_4x4x1_16b_f32 v[232:235], v191, v38, v[232:235]
	v_mfma_f32_4x4x1_16b_f32 v[236:239], v191, v39, v[236:239]
	s_nop 0
	ds_read_b128 v[174:177], v254 offset:800
	ds_read_b128 v[188:191], v254 offset:816
	s_nop 4
	v_fma_f32 v166, v42, v164, v232
	v_fma_f32 v167, v43, v165, v236
	v_fma_f32 v166, v70, v165, v166
	v_fma_f32 v167, v71, v164, v167
	v_fma_f32 v168, v42, v166, v233
	v_fma_f32 v169, v43, v167, v237
	v_fma_f32 v168, v70, v167, v168
	v_fma_f32 v169, v71, v166, v169
	v_fma_f32 v170, v42, v168, v234
	v_fma_f32 v171, v43, v169, v238
	v_fma_f32 v170, v70, v169, v170
	v_fma_f32 v171, v71, v168, v171
	v_fma_f32 v172, v42, v170, v235
	v_fma_f32 v173, v43, v171, v239
	v_fma_f32 v172, v70, v171, v172
	v_fma_f32 v173, v71, v170, v173
	s_waitcnt lgkmcnt(2)
	v_mfma_f32_4x4x1_16b_f32 v[232:235], v20, v72, 0
	v_mfma_f32_4x4x1_16b_f32 v[236:239], v20, v73, 0
	s_nop 0
	v_mfma_f32_4x4x1_16b_f32 v[232:235], v21, v64, v[232:235]
	v_mfma_f32_4x4x1_16b_f32 v[236:239], v21, v65, v[236:239]
	s_nop 0
	v_mfma_f32_4x4x1_16b_f32 v[232:235], v22, v60, v[232:235]
	v_mfma_f32_4x4x1_16b_f32 v[236:239], v22, v61, v[236:239]
	s_nop 0
	v_mfma_f32_4x4x1_16b_f32 v[232:235], v23, v62, v[232:235]
	v_mfma_f32_4x4x1_16b_f32 v[236:239], v23, v63, v[236:239]
	s_nop 0
	v_mfma_f32_4x4x1_16b_f32 v[232:235], v244, v66, v[232:235]
	v_mfma_f32_4x4x1_16b_f32 v[236:239], v244, v67, v[236:239]
	s_nop 0
	v_mfma_f32_4x4x1_16b_f32 v[232:235], v245, v52, v[232:235]
	v_mfma_f32_4x4x1_16b_f32 v[236:239], v245, v53, v[236:239]
	s_nop 0
	v_mfma_f32_4x4x1_16b_f32 v[232:235], v248, v56, v[232:235]
	v_mfma_f32_4x4x1_16b_f32 v[236:239], v248, v57, v[236:239]
	s_nop 0
	v_mfma_f32_4x4x1_16b_f32 v[232:235], v249, v54, v[232:235]
	v_mfma_f32_4x4x1_16b_f32 v[236:239], v249, v55, v[236:239]
	s_nop 0
	s_waitcnt lgkmcnt(0)
	v_mfma_f32_4x4x1_16b_f32 v[232:235], v174, v58, v[232:235]
	v_mfma_f32_4x4x1_16b_f32 v[236:239], v174, v59, v[236:239]
	s_nop 0
	v_mfma_f32_4x4x1_16b_f32 v[232:235], v175, v44, v[232:235]
	v_mfma_f32_4x4x1_16b_f32 v[236:239], v175, v45, v[236:239]
	s_nop 0
	v_mfma_f32_4x4x1_16b_f32 v[232:235], v176, v48, v[232:235]
	v_mfma_f32_4x4x1_16b_f32 v[236:239], v176, v49, v[236:239]
	s_nop 0
	v_mfma_f32_4x4x1_16b_f32 v[232:235], v177, v46, v[232:235]
	v_mfma_f32_4x4x1_16b_f32 v[236:239], v177, v47, v[236:239]
	s_nop 0
	v_mfma_f32_4x4x1_16b_f32 v[232:235], v188, v50, v[232:235]
	v_mfma_f32_4x4x1_16b_f32 v[236:239], v188, v51, v[236:239]
	s_nop 0
	v_mfma_f32_4x4x1_16b_f32 v[232:235], v189, v36, v[232:235]
	v_mfma_f32_4x4x1_16b_f32 v[236:239], v189, v37, v[236:239]
	s_nop 0
	v_mfma_f32_4x4x1_16b_f32 v[232:235], v190, v40, v[232:235]
	v_mfma_f32_4x4x1_16b_f32 v[236:239], v190, v41, v[236:239]
	s_nop 0
	v_mfma_f32_4x4x1_16b_f32 v[232:235], v191, v38, v[232:235]
	v_mfma_f32_4x4x1_16b_f32 v[236:239], v191, v39, v[236:239]
	s_nop 0
	s_nop 4
	v_fma_f32 v174, v42, v172, v232
	v_fma_f32 v175, v43, v173, v236
	v_fma_f32 v174, v70, v173, v174
	v_fma_f32 v175, v71, v172, v175
	v_fma_f32 v176, v42, v174, v233
	v_fma_f32 v177, v43, v175, v237
	v_fma_f32 v176, v70, v175, v176
	v_fma_f32 v177, v71, v174, v177
	v_fma_f32 v188, v42, v176, v234
	v_fma_f32 v189, v43, v177, v238
	v_fma_f32 v188, v70, v177, v188
	v_fma_f32 v189, v71, v176, v189
	v_fma_f32 v190, v42, v188, v235
	v_fma_f32 v191, v43, v189, v239
	v_fma_f32 v190, v70, v189, v190
	v_fma_f32 v191, v71, v188, v191
	v_cndmask_b32_e64 v22, 0, v132, s[0:1]
	ds_write_b64 v217, v[190:191] offset:16384
	s_waitcnt lgkmcnt(0)
	s_barrier
; #define LAS __attribute__((address_space(3)))
; __device__ __forceinline__ unsigned cvt_pk_bf16(float lo, float hi) { unsigned r; asm("v_cvt_pk_bf16_f32 %0, %1, %2" : "=v"(r) : "v"(lo), "v"(hi)); return r; }
; template <bool SAMPLE>
; __device__ __forceinline__ void ssm_item(kp_t kp, LAS unsigned char* lds, int l, int item, const bf16_t* Z, float* YM, int tid, int lane, int wave) {
;     ...
;         Eb[wave * 64 + p] = h;
;         __syncthreads();
; #pragma unroll
;         for (int v = 0; v < 8; ++v) { if (v == wave) { cwr = cr_; cwi = ci_; } const f32x2 e = Eb[v * 64 + p];
;             const float nr = l16r * cr_ - l16i * ci_ + e.x, ni = l16r * ci_ + l16i * cr_ + e.y; cr_ = nr; ci_ = ni; }
;         car = cr_; cai = ci_;
;         }
; #pragma unroll
;         for (int tt = 0; tt < 16; ++tt) {
;             const f32x2 t1 = __builtin_elementwise_fma(pw[tt], (f32x2){cwr, cwr}, hl[tt]);
;             const f32x2 h2 = __builtin_elementwise_fma((f32x2){-pw[tt].y, pw[tt].x}, (f32x2){cwi, cwi}, t1);
;             *(LAS unsigned*)(Hb + (wave * 16 + tt) * 272 + p * 4) = cvt_pk_bf16(h2.x, h2.y); }
	ds_read2st64_b64 v[232:235], v218 offset0:32 offset1:33
	ds_read2st64_b64 v[236:239], v218 offset0:34 offset1:35
	v_mul_f32_e32 v20, v109, v133
	v_pk_fma_f32 v[20:21], v[108:109], v[132:133], v[20:21] op_sel_hi:[1,1,0] neg_lo:[0,0,1] neg_hi:[0,0,1]
	v_pk_fma_f32 v[132:133], v[106:107], v[132:133], v[246:247] op_sel_hi:[1,1,0]
	s_waitcnt lgkmcnt(1)
	v_pk_add_f32 v[244:245], v[20:21], v[232:233]
	v_pk_add_f32 v[132:133], v[132:133], v[232:233] op_sel:[0,1] op_sel_hi:[1,0]
	v_cndmask_b32_e64 v248, v22, v244, s[16:17]
	v_cndmask_b32_e64 v246, v247, v132, s[16:17]
	v_pk_mul_f32 v[132:133], v[106:107], v[132:133] op_sel_hi:[1,0]
	ds_read2st64_b64 v[240:243], v218 offset0:36 offset1:37
	ds_read2st64_b64 v[20:23], v218 offset0:38 offset1:39
	v_add_u32_e32 v217, s84, v217
	v_add_u32_e32 v218, s84, v218
	s_sub_i32 s84, 0, s84
	v_pk_fma_f32 v[232:233], v[108:109], v[244:245], v[132:133] neg_lo:[0,0,1] neg_hi:[0,0,1]
	v_pk_fma_f32 v[132:133], v[108:109], v[244:245], v[132:133] op_sel_hi:[1,0,1]
	s_nop 0
	v_mov_b32_e32 v233, v133
	v_pk_add_f32 v[132:133], v[234:235], v[232:233]
	s_nop 0
	v_cndmask_b32_e64 v235, v248, v132, s[4:5]
	v_mul_f32_e32 v232, v109, v133
	v_mul_f32_e32 v234, v106, v132
	v_cndmask_b32_e64 v244, v246, v133, s[4:5]
	v_pk_fma_f32 v[232:233], v[108:109], v[132:133], v[232:233] op_sel_hi:[1,1,0] neg_lo:[0,0,1] neg_hi:[0,0,1]
	v_pk_fma_f32 v[132:133], v[106:107], v[132:133], v[234:235] op_sel_hi:[1,1,0]
	s_nop 0
	v_mov_b32_e32 v233, v133
	s_waitcnt lgkmcnt(2)
	v_pk_add_f32 v[132:133], v[236:237], v[232:233]
	s_nop 0
	v_pk_mul_f32 v[232:233], v[102:103], v[132:133]
	v_cndmask_b32_e64 v236, v235, v132, s[6:7]
	v_cndmask_b32_e64 v237, v244, v133, s[6:7]
	v_pk_fma_f32 v[234:235], v[104:105], v[132:133], v[232:233] op_sel:[0,0,1] op_sel_hi:[1,1,0] neg_lo:[0,0,1] neg_hi:[0,0,1]
	v_pk_fma_f32 v[132:133], v[104:105], v[132:133], v[232:233] op_sel:[0,0,1] op_sel_hi:[1,1,0]
	s_nop 0
	v_mov_b32_e32 v235, v133
	v_pk_add_f32 v[132:133], v[238:239], v[234:235]
	s_nop 0
	v_pk_mul_f32 v[232:233], v[102:103], v[132:133]
	v_cndmask_b32_e64 v236, v236, v132, s[8:9]
	v_cndmask_b32_e64 v237, v237, v133, s[8:9]
	v_pk_fma_f32 v[234:235], v[104:105], v[132:133], v[232:233] op_sel:[0,0,1] op_sel_hi:[1,1,0] neg_lo:[0,0,1] neg_hi:[0,0,1]
	v_pk_fma_f32 v[132:133], v[104:105], v[132:133], v[232:233] op_sel:[0,0,1] op_sel_hi:[1,1,0]
	s_nop 0
	v_mov_b32_e32 v235, v133
	s_waitcnt lgkmcnt(1)
	v_pk_add_f32 v[132:133], v[240:241], v[234:235]
	s_nop 0
	v_pk_mul_f32 v[232:233], v[102:103], v[132:133]
	v_cndmask_b32_e64 v236, v236, v132, s[10:11]
	v_cndmask_b32_e64 v237, v237, v133, s[10:11]
	v_pk_fma_f32 v[234:235], v[104:105], v[132:133], v[232:233] op_sel:[0,0,1] op_sel_hi:[1,1,0] neg_lo:[0,0,1] neg_hi:[0,0,1]
	v_pk_fma_f32 v[132:133], v[104:105], v[132:133], v[232:233] op_sel:[0,0,1] op_sel_hi:[1,1,0]
	s_nop 0
	v_mov_b32_e32 v235, v133
	v_pk_add_f32 v[232:233], v[242:243], v[234:235]
	s_nop 0
	v_mul_f32_e32 v132, v109, v233
	v_cndmask_b32_e64 v235, v236, v232, s[12:13]
	v_pk_fma_f32 v[132:133], v[108:109], v[232:233], v[132:133] op_sel_hi:[1,1,0] neg_lo:[0,0,1] neg_hi:[0,0,1]
	v_mul_f32_e32 v234, v107, v233
	v_cndmask_b32_e64 v236, v237, v233, s[12:13]
	s_waitcnt lgkmcnt(0)
	v_pk_add_f32 v[132:133], v[20:21], v[132:133]
	v_pk_fma_f32 v[232:233], v[106:107], v[232:233], v[234:235] op_sel_hi:[1,1,0]
	s_nop 0
	v_pk_add_f32 v[20:21], v[20:21], v[232:233] op_sel:[1,0] op_sel_hi:[0,1]
	v_cndmask_b32_e64 v232, v235, v132, s[14:15]
	v_cndmask_b32_e64 v234, v236, v20, s[14:15]
	v_pk_fma_f32 v[138:139], v[68:69], v[232:233], v[138:139] op_sel_hi:[1,0,1]
	v_pk_mul_f32 v[20:21], v[106:107], v[20:21] op_sel_hi:[1,0]
	v_pk_fma_f32 v[138:139], v[26:27], v[234:235], v[138:139] op_sel_hi:[1,0,1]
	s_nop 0
	v_cvt_pk_bf16_f32 v233, v138, v139
	s_nop 0
	v_pk_fma_f32 v[138:139], v[74:75], v[232:233], v[140:141] op_sel_hi:[1,0,1]
	v_add_u32_e32 v140, 0x5000, v148
	v_pk_fma_f32 v[138:139], v[28:29], v[234:235], v[138:139] op_sel_hi:[1,0,1]
	s_nop 0
	v_cvt_pk_bf16_f32 v138, v138, v139
	ds_write2_b32 v140, v233, v138 offset1:68
	v_pk_fma_f32 v[138:139], v[76:77], v[232:233], v[142:143] op_sel_hi:[1,0,1]
	s_nop 0
	v_pk_fma_f32 v[138:139], v[30:31], v[234:235], v[138:139] op_sel_hi:[1,0,1]
	s_nop 0
	v_cvt_pk_bf16_f32 v141, v138, v139
	v_pk_fma_f32 v[138:139], v[78:79], v[232:233], v[144:145] op_sel_hi:[1,0,1]
	s_nop 0
	v_pk_fma_f32 v[138:139], v[32:33], v[234:235], v[138:139] op_sel_hi:[1,0,1]
	s_nop 0
	v_cvt_pk_bf16_f32 v138, v138, v139
	ds_write2_b32 v140, v141, v138 offset0:136 offset1:204
	v_pk_fma_f32 v[138:139], v[80:81], v[232:233], v[146:147] op_sel_hi:[1,0,1]
	v_add_u32_e32 v141, 0x5400, v148
	v_pk_fma_f32 v[138:139], v[34:35], v[234:235], v[138:139] op_sel_hi:[1,0,1]
	v_lshl_add_u32 v146, v219, 2, s3
	v_cvt_pk_bf16_f32 v140, v138, v139
	v_pk_fma_f32 v[138:139], v[82:83], v[232:233], v[160:161] op_sel_hi:[1,0,1]
	s_nop 0
	v_pk_fma_f32 v[138:139], v[110:111], v[234:235], v[138:139] op_sel_hi:[1,0,1]
	s_nop 0
	v_cvt_pk_bf16_f32 v138, v138, v139
	ds_write2_b32 v141, v140, v138 offset0:16 offset1:84
	v_pk_fma_f32 v[138:139], v[84:85], v[232:233], v[162:163] op_sel_hi:[1,0,1]
	s_nop 0
	v_pk_fma_f32 v[138:139], v[112:113], v[234:235], v[138:139] op_sel_hi:[1,0,1]
	s_nop 0
	v_cvt_pk_bf16_f32 v140, v138, v139
	v_pk_fma_f32 v[138:139], v[86:87], v[232:233], v[164:165] op_sel_hi:[1,0,1]
	s_nop 0
	v_pk_fma_f32 v[138:139], v[114:115], v[234:235], v[138:139] op_sel_hi:[1,0,1]
	s_nop 0
	v_cvt_pk_bf16_f32 v138, v138, v139
	ds_write2_b32 v141, v140, v138 offset0:152 offset1:220
	v_pk_fma_f32 v[138:139], v[88:89], v[232:233], v[166:167] op_sel_hi:[1,0,1]
	v_add_u32_e32 v141, 0x5800, v148
; #define LAS __attribute__((address_space(3)))
; __device__ __forceinline__ unsigned cvt_pk_bf16(float lo, float hi) { unsigned r; asm("v_cvt_pk_bf16_f32 %0, %1, %2" : "=v"(r) : "v"(lo), "v"(hi)); return r; }
; #define LDS_WAIT() asm volatile("s_waitcnt lgkmcnt(0)" ::: "memory")
; template <bool SAMPLE>
; __device__ __forceinline__ void ssm_item(kp_t kp, LAS unsigned char* lds, int l, int item, const bf16_t* Z, float* YM, int tid, int lane, int wave) {
;     ...
;         for (int tt = 0; tt < 16; ++tt) {
;             const f32x2 t1 = __builtin_elementwise_fma(pw[tt], (f32x2){cwr, cwr}, hl[tt]);
;             const f32x2 h2 = __builtin_elementwise_fma((f32x2){-pw[tt].y, pw[tt].x}, (f32x2){cwi, cwi}, t1);
;             *(LAS unsigned*)(Hb + (wave * 16 + tt) * 272 + p * 4) = cvt_pk_bf16(h2.x, h2.y); }
;         LDS_WAIT();
;         f32x4 acc = (f32x4){0.f, 0.f, 0.f, 0.f};
; #pragma unroll
;         for (int ks = 0; ks < 4; ++ks) { const bf16x8 av = *(const LAS bf16x8*)(Hb + (wave * 16 + fr) * 272 + (ks * 32 + fq * 8) * 2);
;             acc = __builtin_amdgcn_mfma_f32_16x16x32_bf16(av, cf[ks], acc, 0, 0, 0); }
;         float yv[4];
; #pragma unroll
;         for (int j = 0; j < 4; ++j) { const int t = wave * 16 + fq * 4 + j; float y = acc[j] + Dv * U[t * 16 + fr]; y = gelu_tanh(y); yv[j] = y; Yb[t * 16 + fr] = y; }
	v_pk_fma_f32 v[138:139], v[116:117], v[234:235], v[138:139] op_sel_hi:[1,0,1]
	s_nop 0
	v_cvt_pk_bf16_f32 v140, v138, v139
	v_pk_fma_f32 v[138:139], v[90:91], v[232:233], v[168:169] op_sel_hi:[1,0,1]
	s_nop 0
	v_pk_fma_f32 v[138:139], v[118:119], v[234:235], v[138:139] op_sel_hi:[1,0,1]
	s_nop 0
	v_cvt_pk_bf16_f32 v138, v138, v139
	ds_write2_b32 v141, v140, v138 offset0:32 offset1:100
	v_pk_fma_f32 v[138:139], v[92:93], v[232:233], v[170:171] op_sel_hi:[1,0,1]
	s_nop 0
	v_pk_fma_f32 v[138:139], v[120:121], v[234:235], v[138:139] op_sel_hi:[1,0,1]
	s_nop 0
	v_cvt_pk_bf16_f32 v140, v138, v139
	v_pk_fma_f32 v[138:139], v[94:95], v[232:233], v[172:173] op_sel_hi:[1,0,1]
	s_nop 0
	v_pk_fma_f32 v[138:139], v[122:123], v[234:235], v[138:139] op_sel_hi:[1,0,1]
	s_nop 0
	v_cvt_pk_bf16_f32 v138, v138, v139
	ds_write2_b32 v141, v140, v138 offset0:168 offset1:236
	v_pk_fma_f32 v[138:139], v[96:97], v[232:233], v[174:175] op_sel_hi:[1,0,1]
	v_add_u32_e32 v141, 0x5c00, v148
	v_pk_fma_f32 v[138:139], v[124:125], v[234:235], v[138:139] op_sel_hi:[1,0,1]
	s_nop 0
	v_cvt_pk_bf16_f32 v140, v138, v139
	v_pk_fma_f32 v[138:139], v[98:99], v[232:233], v[176:177] op_sel_hi:[1,0,1]
	s_nop 0
	v_pk_fma_f32 v[138:139], v[126:127], v[234:235], v[138:139] op_sel_hi:[1,0,1]
	s_nop 0
	v_cvt_pk_bf16_f32 v138, v138, v139
	ds_write2_b32 v141, v140, v138 offset0:48 offset1:116
	v_pk_fma_f32 v[138:139], v[100:101], v[232:233], v[188:189] op_sel_hi:[1,0,1]
	s_nop 0
	v_pk_fma_f32 v[138:139], v[128:129], v[234:235], v[138:139] op_sel_hi:[1,0,1]
	s_nop 0
	v_cvt_pk_bf16_f32 v140, v138, v139
	v_pk_fma_f32 v[138:139], v[108:109], v[232:233], v[190:191] op_sel_hi:[1,0,1]
	s_nop 0
	v_pk_fma_f32 v[138:139], v[130:131], v[234:235], v[138:139] op_sel_hi:[1,0,1]
	s_nop 0
	v_cvt_pk_bf16_f32 v138, v138, v139
	ds_write2_b32 v141, v140, v138 offset0:184 offset1:252
	s_waitcnt lgkmcnt(0)
	ds_read_b128 v[138:141], v227 offset:20480
	ds_read_b128 v[142:145], v227 offset:20544
	s_waitcnt lgkmcnt(1)
	v_mfma_f32_16x16x32_bf16 v[138:141], v[138:141], v[4:7], 0
	ds_read_b128 v[160:163], v227 offset:20608
	ds_read_b32 v146, v146
	s_waitcnt lgkmcnt(2)
	v_mfma_f32_16x16x32_bf16 v[138:141], v[142:145], v[8:11], v[138:141]
	ds_read_b128 v[142:145], v227 offset:20672
	s_waitcnt lgkmcnt(2)
	v_mfma_f32_16x16x32_bf16 v[138:141], v[160:163], v[12:15], v[138:141]
	s_waitcnt lgkmcnt(0)
	v_mfma_f32_16x16x32_bf16 v[138:141], v[142:145], v[16:19], v[138:141]
	s_nop 7
	v_fma_f32 v138, v200, v146, v138
	v_mul_f32_e32 v142, 0x3d372713, v138
	v_mul_f32_e32 v142, v138, v142
	v_fma_f32 v142, v138, v142, v138
	v_mul_f32_e32 v142, 0x3f4c422a, v142
	v_add_f32_e32 v142, v142, v142
	v_mul_f32_e32 v142, 0x3fb8aa3b, v142
	v_exp_f32_e32 v142, v142
	v_mul_f32_e32 v138, 0.5, v138
	v_add_f32_e32 v142, 1.0, v142
	v_div_scale_f32 v143, s[26:27], v142, v142, 2.0
	v_rcp_f32_e32 v144, v143
	s_nop 0
	v_fma_f32 v145, -v143, v144, 1.0
	v_fmac_f32_e32 v144, v145, v144
	v_div_scale_f32 v145, vcc, 2.0, v142, 2.0
	v_mul_f32_e32 v146, v145, v144
	v_fma_f32 v147, -v143, v146, v145
	v_fmac_f32_e32 v146, v147, v144
	v_fma_f32 v143, -v143, v146, v145
	v_div_fmas_f32 v143, v143, v144, v146
	v_div_fixup_f32 v142, v143, v142, 2.0
	v_sub_f32_e32 v142, 1.0, v142
	v_add_f32_e32 v142, 1.0, v142
	v_mul_f32_e32 v168, v138, v142
	ds_write_b32 v220, v168 offset:55296
	v_lshl_add_u32 v138, v221, 2, s3
	ds_read_b32 v138, v138
	s_waitcnt lgkmcnt(0)
	v_fma_f32 v138, v200, v138, v139
	v_mul_f32_e32 v139, 0x3d372713, v138
	v_mul_f32_e32 v139, v138, v139
	v_fma_f32 v139, v138, v139, v138
	v_mul_f32_e32 v139, 0x3f4c422a, v139
	v_add_f32_e32 v139, v139, v139
	v_mul_f32_e32 v139, 0x3fb8aa3b, v139
	v_exp_f32_e32 v139, v139
	v_mul_f32_e32 v138, 0.5, v138
	v_add_f32_e32 v139, 1.0, v139
	v_div_scale_f32 v142, s[26:27], v139, v139, 2.0
	v_rcp_f32_e32 v143, v142
	s_nop 0
	v_fma_f32 v144, -v142, v143, 1.0
	v_fmac_f32_e32 v143, v144, v143
	v_div_scale_f32 v144, vcc, 2.0, v139, 2.0
	v_mul_f32_e32 v145, v144, v143
	v_fma_f32 v146, -v142, v145, v144
	v_fmac_f32_e32 v145, v146, v143
	v_fma_f32 v142, -v142, v145, v144
	v_div_fmas_f32 v142, v142, v143, v145
	v_div_fixup_f32 v139, v142, v139, 2.0
	v_sub_f32_e32 v139, 1.0, v139
	v_add_f32_e32 v139, 1.0, v139
	v_mul_f32_e32 v169, v138, v139
	ds_write_b32 v222, v169 offset:55296
	v_lshl_add_u32 v138, v223, 2, s3
	ds_read_b32 v138, v138
	v_pk_fma_f32 v[146:147], v[108:109], v[132:133], v[20:21] neg_lo:[0,0,1] neg_hi:[0,0,1]
	v_pk_fma_f32 v[20:21], v[108:109], v[132:133], v[20:21] op_sel_hi:[1,0,1]
	s_waitcnt lgkmcnt(0)
	v_fma_f32 v138, v200, v138, v140
	v_mul_f32_e32 v139, 0x3d372713, v138
	v_mul_f32_e32 v139, v138, v139
	v_fma_f32 v139, v138, v139, v138
	v_mul_f32_e32 v139, 0x3f4c422a, v139
	v_add_f32_e32 v139, v139, v139
	v_mul_f32_e32 v139, 0x3fb8aa3b, v139
	v_exp_f32_e32 v139, v139
	v_mul_f32_e32 v138, 0.5, v138
	v_mov_b32_e32 v147, v21
	v_add_f32_e32 v139, 1.0, v139
	v_div_scale_f32 v140, s[26:27], v139, v139, 2.0
	v_rcp_f32_e32 v142, v140
	s_nop 0
	v_fma_f32 v143, -v140, v142, 1.0
	v_fmac_f32_e32 v142, v143, v142
	v_div_scale_f32 v143, vcc, 2.0, v139, 2.0
	v_mul_f32_e32 v144, v143, v142
	v_fma_f32 v145, -v140, v144, v143
	v_fmac_f32_e32 v144, v145, v142
	v_fma_f32 v140, -v140, v144, v143
	v_div_fmas_f32 v140, v140, v142, v144
	v_div_fixup_f32 v139, v140, v139, 2.0
	v_sub_f32_e32 v139, 1.0, v139
	v_add_f32_e32 v139, 1.0, v139
	v_mul_f32_e32 v170, v138, v139
	ds_write_b32 v224, v170 offset:55296
	v_lshl_add_u32 v138, v225, 2, s3
	ds_read_b32 v138, v138
	s_mov_b32 s3, 0x10d00000
	s_waitcnt lgkmcnt(0)
; #define LAS __attribute__((address_space(3)))
; #define LDS_WAIT() asm volatile("s_waitcnt lgkmcnt(0)" ::: "memory")
; __device__ __forceinline__ float sigmoidf(float s) { return 1.0f / (1.0f + __expf(-s)); }
; template <bool SAMPLE>
; __device__ __forceinline__ void ssm_item(kp_t kp, LAS unsigned char* lds, int l, int item, const bf16_t* Z, float* YM, int tid, int lane, int wave) {
;     ...
;         for (int j = 0; j < 4; ++j) { const int t = wave * 16 + fq * 4 + j; float y = acc[j] + Dv * U[t * 16 + fr]; y = gelu_tanh(y); yv[j] = y; Yb[t * 16 + fr] = y; }
;         LDS_WAIT();
; #pragma unroll
;         for (int j = 0; j < 4; ++j) { const int t = wave * 16 + fq * 4 + j; const LAS f32x4* yp = (const LAS f32x4*)(Yb + t * 16); float s = 0.f;
; #pragma unroll
;             for (int q = 0; q < 4; ++q) { const f32x4 v = yp[q]; s += (v[0] * wg[4 * q] + v[1] * wg[4 * q + 1]) + (v[2] * wg[4 * q + 2] + v[3] * wg[4 * q + 3]); }
;             YM[(tok0 + t) * DM + g * 16 + fr] = yv[j] * sigmoidf(s); }
	v_fmac_f32_e32 v141, v200, v138
	v_mul_f32_e32 v138, 0x3d372713, v141
	v_mul_f32_e32 v138, v141, v138
	v_fma_f32 v138, v141, v138, v141
	v_mul_f32_e32 v138, 0x3f4c422a, v138
	v_add_f32_e32 v138, v138, v138
	v_mul_f32_e32 v138, 0x3fb8aa3b, v138
	v_exp_f32_e32 v138, v138
	s_nop 0
	v_add_f32_e32 v138, 1.0, v138
	v_div_scale_f32 v139, s[26:27], v138, v138, 2.0
	v_rcp_f32_e32 v140, v139
	s_nop 0
	v_fma_f32 v142, -v139, v140, 1.0
	v_fmac_f32_e32 v140, v142, v140
	v_div_scale_f32 v142, vcc, 2.0, v138, 2.0
	v_mul_f32_e32 v143, v142, v140
	v_fma_f32 v144, -v139, v143, v142
	v_fmac_f32_e32 v143, v144, v140
	v_fma_f32 v139, -v139, v143, v142
	v_div_fmas_f32 v139, v139, v140, v143
	v_div_fixup_f32 v138, v139, v138, 2.0
	v_sub_f32_e32 v138, 1.0, v138
	v_mul_f32_e32 v139, 0.5, v141
	v_add_f32_e32 v138, 1.0, v138
	v_mul_f32_e32 v171, v139, v138
	ds_write_b32 v226, v171 offset:55296
	s_waitcnt lgkmcnt(0)
	v_and_b32_e32 v172, 15, v184
	v_lshrrev_b32_e32 v20, 4, v184
	v_lshlrev_b32_e32 v172, 6, v172
	v_lshl_add_u32 v172, v20, 4, v172
	v_add_u32_e32 v172, s24, v172
	ds_read_b128 v[138:141], v172 offset:55296
	v_cmp_eq_u32_e64 s[86:87], 1, v20
	v_cmp_eq_u32_e64 s[88:89], 2, v20
	v_cmp_eq_u32_e64 s[90:91], 3, v20
	s_nop 1
	v_cndmask_b32_e64 v142, v201, v205, s[86:87]
	v_cndmask_b32_e64 v143, v202, v206, s[86:87]
	v_cndmask_b32_e64 v144, v203, v207, s[86:87]
	v_cndmask_b32_e64 v145, v204, v208, s[86:87]
	v_cndmask_b32_e64 v142, v142, v209, s[88:89]
	v_cndmask_b32_e64 v143, v143, v210, s[88:89]
	v_cndmask_b32_e64 v144, v144, v211, s[88:89]
	v_cndmask_b32_e64 v145, v145, v212, s[88:89]
	v_cndmask_b32_e64 v142, v142, v213, s[90:91]
	v_cndmask_b32_e64 v143, v143, v214, s[90:91]
	v_cndmask_b32_e64 v144, v144, v215, s[90:91]
	v_cndmask_b32_e64 v145, v145, v216, s[90:91]
	s_waitcnt lgkmcnt(0)
	s_nop 1
	v_mfma_f32_16x16x4_f32 v[160:163], v138, v142, 0
	v_mfma_f32_16x16x4_f32 v[160:163], v139, v143, v[160:163]
	v_mfma_f32_16x16x4_f32 v[160:163], v140, v144, v[160:163]
	v_mfma_f32_16x16x4_f32 v[160:163], v141, v145, v[160:163]
	s_nop 11
	v_mul_f32_e32 v138, 0xbfb8aa3b, v160
	v_exp_f32_e32 v138, v138
	s_nop 0
	v_add_f32_e32 v172, 1.0, v138
	v_div_scale_f32 v138, s[26:27], v172, v172, 1.0
	v_rcp_f32_e32 v142, v138
	s_nop 0
	v_fma_f32 v20, -v138, v142, 1.0
	v_fmac_f32_e32 v142, v20, v142
	v_div_scale_f32 v20, vcc, 1.0, v172, 1.0
	v_mul_f32_e32 v21, v20, v142
	v_fma_f32 v132, -v138, v21, v20
	v_fmac_f32_e32 v21, v132, v142
	v_fma_f32 v20, -v138, v21, v20
	v_div_fmas_f32 v20, v20, v142, v21
	v_div_fixup_f32 v20, v20, v172, 1.0
	v_mul_f32_e32 v21, 0xbfb8aa3b, v161
	v_exp_f32_e32 v132, v21
	v_mul_f32_e32 v138, v168, v20
	v_lshl_add_u64 v[20:21], v[136:137], 0, s[20:21]
	s_add_u32 s20, s20, 0x100000
	v_add_f32_e32 v168, 1.0, v132
	v_div_scale_f32 v142, s[26:27], v168, v168, 1.0
	v_rcp_f32_e32 v172, v142
	v_add_co_u32_e32 v132, vcc, s3, v20
	s_mov_b32 s3, 0x10d02000
	s_nop 0
	v_addc_co_u32_e32 v133, vcc, 0, v21, vcc
	s_waitcnt vmcnt(0)
	v_lshlrev_b32_e32 v0, 16, v2
	v_and_b32_e32 v1, 0xffff0000, v2
	v_lshlrev_b32_e32 v2, 16, v3
	v_and_b32_e32 v3, 0xffff0000, v3
	global_store_dword v[132:133], v138, off
	v_fma_f32 v132, -v142, v172, 1.0
	v_fmac_f32_e32 v172, v132, v172
	v_div_scale_f32 v132, vcc, 1.0, v168, 1.0
	v_mul_f32_e32 v133, v132, v172
	v_fma_f32 v138, -v142, v133, v132
	v_fmac_f32_e32 v133, v138, v172
	v_fma_f32 v132, -v142, v133, v132
	v_div_fmas_f32 v132, v132, v172, v133
	v_div_fixup_f32 v132, v132, v168, 1.0
	v_mul_f32_e32 v138, 0xbfb8aa3b, v162
	v_exp_f32_e32 v138, v138
	v_mul_f32_e32 v139, v169, v132
	v_add_co_u32_e32 v132, vcc, s3, v20
	v_add_f32_e32 v168, 1.0, v138
	v_div_scale_f32 v142, s[26:27], v168, v168, 1.0
	v_rcp_f32_e32 v169, v142
	v_addc_co_u32_e32 v133, vcc, 0, v21, vcc
	global_store_dword v[132:133], v139, off
	v_fma_f32 v132, -v142, v169, 1.0
	v_fmac_f32_e32 v169, v132, v169
	v_div_scale_f32 v132, vcc, 1.0, v168, 1.0
	v_mul_f32_e32 v133, v132, v169
	v_fma_f32 v138, -v142, v133, v132
	v_fmac_f32_e32 v133, v138, v169
	v_fma_f32 v132, -v142, v133, v132
	v_div_fmas_f32 v132, v132, v169, v133
	v_div_fixup_f32 v132, v132, v168, 1.0
	v_mul_f32_e32 v138, 0xbfb8aa3b, v163
	v_exp_f32_e32 v138, v138
	s_mov_b32 s3, 0x10d04000
	v_mul_f32_e32 v139, v170, v132
	v_add_co_u32_e32 v132, vcc, s3, v20
	v_add_f32_e32 v138, 1.0, v138
	v_div_scale_f32 v140, s[26:27], v138, v138, 1.0
	v_rcp_f32_e32 v141, v140
	v_addc_co_u32_e32 v133, vcc, 0, v21, vcc
	global_store_dword v[132:133], v139, off
	v_fma_f32 v132, -v140, v141, 1.0
	v_fmac_f32_e32 v141, v132, v141
	v_div_scale_f32 v132, vcc, 1.0, v138, 1.0
	v_mul_f32_e32 v133, v132, v141
	v_fma_f32 v139, -v140, v133, v132
	v_fmac_f32_e32 v133, v139, v141
	v_fma_f32 v132, -v140, v133, v132
	v_div_fmas_f32 v132, v132, v141, v133
	s_mov_b32 s3, 0x10d06000
	v_div_fixup_f32 v132, v132, v138, 1.0
	v_add_co_u32_e32 v20, vcc, s3, v20
	v_mul_f32_e32 v132, v171, v132
	s_nop 0
	v_addc_co_u32_e32 v21, vcc, 0, v21, vcc
	global_store_dword v[20:21], v132, off
	s_waitcnt lgkmcnt(0)
	s_addc_u32 s21, s21, 0
	s_addk_i32 s23, 0x800
	s_mov_b64 s[26:27], 0xa0000
	v_pk_add_f32 v[132:133], v[22:23], v[146:147]
	s_cmp_eq_u32 s20, 0x1000000
	v_lshl_add_u64 v[134:135], v[134:135], 0, s[26:27]
	s_cbranch_scc1 .LBB0_103
